# SEAM4 (P4->P5) grid barrier replaced by a 4-workgroup same-XCD arrival counter (guarded by an XCC_ID placement check, falls back to the grid barrier)
# speedup vs baseline: 1.0006x; 1.0001x over previous
.LBB0_30:
	s_cmp_gt_i32 s91, 1
	s_cselect_b64 s[4:5], -1, 0
	s_and_b64 s[6:7], s[6:7], s[4:5]
	s_andn2_b64 vcc, exec, s[6:7]
	s_cbranch_vccnz .LBB0_85
	s_waitcnt vmcnt(0) lgkmcnt(0)
	s_barrier
	v_readlane_b32 s6, v255, 2
	v_readlane_b32 s7, v255, 3
	s_mov_b64 s[8:9], exec
	s_and_b64 exec, exec, s[6:7]
	s_cbranch_execz .Lp0_arrived
	v_mov_b32_e32 v0, 0
	v_mov_b32_e32 v1, 1
	global_atomic_add v0, v1, s[88:89] offset:2048
	s_getreg_b32 s98, hwreg(HW_REG_XCC_ID, 0, 4)
	s_and_b32 s99, s2, 7
	s_cmp_lg_u32 s98, s99
	s_cbranch_scc1 .Lp0_badplace
	s_cmpk_eq_u32 s33, 0x100
	s_cbranch_scc1 .Lp0_arrived
.Lp0_badplace:
	v_mov_b32_e32 v0, 0xe000
	global_atomic_add v0, v1, s[88:89]

.LBB0_511:
	s_cmp_gt_i32 s91, 5
	s_cselect_b64 s[4:5], -1, 0
	s_and_b64 s[0:1], s[0:1], s[4:5]
	s_andn2_b64 vcc, exec, s[0:1]
	s_cbranch_vccnz .LBB0_565
	s_waitcnt vmcnt(0)
	s_waitcnt vmcnt(0) lgkmcnt(0)
	s_barrier
	s_and_saveexec_b64 s[0:1], s[84:85]
	s_cbranch_execz .LBB0_564
	v_mov_b32_e32 v0, 0xe000
	global_load_dword v1, v0, s[88:89] sc1
	s_and_b32 s98, s2, 7
	s_lshl_b32 s98, s98, 3
	s_bfe_u32 s99, s2, 0x30003
	s_add_i32 s98, s98, s99
	s_lshl_b32 s98, s98, 6
	s_add_i32 s98, s98, 0xd000
	v_mov_b32_e32 v2, s98
	v_mov_b32_e32 v3, 1
	s_waitcnt vmcnt(0)
	v_cmp_ne_u32_e32 vcc, 0, v1
	s_cbranch_vccnz .Lg4_orig
	global_atomic_add v2, v3, s[88:89]
.Lg4_poll:
	global_load_dword v1, v2, s[88:89] sc1
	s_waitcnt vmcnt(0)
	v_cmp_gt_u32_e32 vcc, 4, v1
	s_cbranch_vccz .LBB0_564
	s_sleep 1
	s_branch .Lg4_poll
.Lg4_orig:
	s_add_i32 s3, 0, 0x23c00
	v_mov_b32_e32 v0, s3
	s_waitcnt vmcnt(0) expcnt(0) lgkmcnt(0)
	ds_read_b32 v2, v0
	s_add_i32 s3, 0, 0x23c04
	v_mov_b32_e32 v0, s3
	ds_read_b32 v0, v0
	s_waitcnt lgkmcnt(1)
	v_cmp_ne_u32_e32 vcc, 0, v2
	s_cbranch_vccnz .LBB0_528
	v_readlane_b32 s6, v255, 0
	v_readlane_b32 s7, v255, 1
	s_load_dwordx2 s[10:11], s[6:7], 0x4
	s_add_u32 s6, s88, 0x10200
	s_addc_u32 s7, s89, 0
	s_add_u32 s8, s88, 0x10400
	s_addc_u32 s9, s89, 0
	s_waitcnt lgkmcnt(0)
	s_mul_i32 s3, s10, s33
	s_add_u32 s10, s88, 0x10500
	s_mul_i32 s3, s3, s11
	s_addc_u32 s11, s89, 0
	s_add_u32 s12, s88, 0x10600
	s_addc_u32 s13, s89, 0
	s_add_u32 s14, s88, 0x10700
	s_addc_u32 s15, s89, 0
	s_add_u32 s16, s88, 0x10800
	s_addc_u32 s17, s89, 0
	s_add_u32 s18, s88, 0x10900
	s_addc_u32 s19, s89, 0
	s_add_u32 s20, s88, 0x10a00
	s_addc_u32 s21, s89, 0
	s_add_u32 s22, s88, 0x10b00
	s_addc_u32 s23, s89, 0
	s_add_u32 s24, s88, 0x10c00
	s_addc_u32 s25, s89, 0
	s_add_u32 s26, s88, 0x10d00
	s_addc_u32 s27, s89, 0
	s_add_u32 s28, s88, 0x10e00
	s_addc_u32 s29, s89, 0
	s_add_u32 s30, s88, 0x10f00
	s_addc_u32 s31, s89, 0
	s_add_u32 s34, s88, 0x11000
	s_addc_u32 s35, s89, 0
	s_add_u32 s36, s88, 0x11100
	s_addc_u32 s37, s89, 0
	s_add_u32 s38, s88, 0x11200
	s_addc_u32 s39, s89, 0
	s_add_u32 s40, s88, 0x11300
	s_addc_u32 s41, s89, 0
	s_mov_b32 s48, 1
	v_mov_b32_e32 v16, 0
	s_branch .LBB0_516
